# one counted LDS wait per step pair
# baseline (speedup 1.0000x reference)
.LBB0_682:
	s_bitcmp1_b32 s30, 0
	s_cselect_b32 s6, 0xe000, 0
	s_add_i32 s6, s6, 0
	v_add_u32_e32 v90, s6, v58
	v_sub_u32_e32 v88, v90, v61
	v_add_u32_e32 v89, s6, v86
	ds_read_b128 v[4:7], v90 offset:0x4000
	ds_read_b128 v[8:11], v90 offset:0x0
	ds_read2st64_b32 v[108:109], v89 offset0:192 offset1:193
	ds_read2st64_b64 v[100:103], v88 offset0:64 offset1:65
	ds_read_b128 v[112:115], v90 offset:0x4200
	ds_read_b128 v[96:99], v90 offset:0x200
	ds_read_b128 v[120:123], v90 offset:0x4400
	ds_read_b128 v[124:127], v90 offset:0x400
	v_mov_b32_e32 v93, v91
	s_waitcnt lgkmcnt(2)
	v_pk_mul_f32 v[0:1], v[52:53], v[4:5] op_sel_hi:[0,1]
	v_pk_fma_f32 v[0:1], v[52:53], v[6:7], v[0:1] op_sel:[1,0,0]
	v_pk_mul_f32 v[10:11], v[108:109], v[10:11] op_sel_hi:[0,1]
	ds_read_b128 v[4:7], v90 offset:0x4600
	v_add_f32_dpp v0, v0, v0 quad_perm:[1,0,3,2] row_mask:0xf bank_mask:0xf bound_ctrl:1
	v_add_f32_dpp v1, v1, v1 quad_perm:[1,0,3,2] row_mask:0xf bank_mask:0xf bound_ctrl:1
	v_pk_fma_f32 v[54:55], v[52:53], v[8:9], v[10:11]
	v_add_f32_dpp v0, v0, v0 quad_perm:[2,3,0,1] row_mask:0xf bank_mask:0xf bound_ctrl:1
	ds_read_b128 v[8:11], v90 offset:0x600
	s_nop 0
	v_add_f32_dpp v0, v0, v0 row_half_mirror row_mask:0xf bank_mask:0xf bound_ctrl:1
	ds_read2st64_b32 v[110:111], v89 offset0:194 offset1:195
	ds_read2st64_b64 v[104:107], v88 offset0:66 offset1:67
	v_add_f32_dpp v2, v0, v0 row_mirror row_mask:0xf bank_mask:0xf bound_ctrl:1
	v_add_f32_dpp v0, v0, v0 row_mirror row_mask:0xf bank_mask:0xf bound_ctrl:1
	s_nop 1
	v_permlane16_swap_b32_e32 v0, v2
	v_add_f32_e32 v0, v0, v2
	v_pk_fma_f32 v[52:53], v[100:101], v[0:1], v[54:55] op_sel_hi:[1,0,1]
	v_pk_mul_f32 v[118:119], v[52:53], v[112:113] op_sel_hi:[0,1]
	v_pk_fma_f32 v[118:119], v[52:53], v[114:115], v[118:119] op_sel:[1,0,0]
	v_pk_mul_f32 v[98:99], v[108:109], v[98:99] op_sel:[1,0]
	ds_read_b128 v[112:115], v90 offset:0x4800
	v_add_f32_dpp v118, v118, v118 quad_perm:[1,0,3,2] row_mask:0xf bank_mask:0xf bound_ctrl:1
	v_add_f32_dpp v119, v119, v119 quad_perm:[1,0,3,2] row_mask:0xf bank_mask:0xf bound_ctrl:1
	v_pk_fma_f32 v[54:55], v[52:53], v[96:97], v[98:99]
	v_add_f32_dpp v118, v118, v118 quad_perm:[2,3,0,1] row_mask:0xf bank_mask:0xf bound_ctrl:1
	ds_read_b128 v[96:99], v90 offset:0x800
	s_nop 0
	v_add_f32_dpp v118, v118, v118 row_half_mirror row_mask:0xf bank_mask:0xf bound_ctrl:1
	ds_write2_b32 v93, v1, v119 offset0:0 offset1:36
	s_nop 0
	v_add_f32_dpp v2, v118, v118 row_mirror row_mask:0xf bank_mask:0xf bound_ctrl:1
	v_add_f32_dpp v118, v118, v118 row_mirror row_mask:0xf bank_mask:0xf bound_ctrl:1
	s_nop 0
	s_waitcnt lgkmcnt(3)
	v_permlane16_swap_b32_e32 v118, v2
	v_add_f32_e32 v118, v118, v2
	v_pk_fma_f32 v[52:53], v[102:103], v[118:119], v[54:55] op_sel_hi:[1,0,1]
	v_pk_mul_f32 v[0:1], v[52:53], v[120:121] op_sel_hi:[0,1]
	v_pk_fma_f32 v[0:1], v[52:53], v[122:123], v[0:1] op_sel:[1,0,0]
	v_pk_mul_f32 v[126:127], v[110:111], v[126:127] op_sel_hi:[0,1]
	ds_read_b128 v[120:123], v90 offset:0x4a00
	v_add_f32_dpp v0, v0, v0 quad_perm:[1,0,3,2] row_mask:0xf bank_mask:0xf bound_ctrl:1
	v_add_f32_dpp v1, v1, v1 quad_perm:[1,0,3,2] row_mask:0xf bank_mask:0xf bound_ctrl:1
	v_pk_fma_f32 v[54:55], v[52:53], v[124:125], v[126:127]
	v_add_f32_dpp v0, v0, v0 quad_perm:[2,3,0,1] row_mask:0xf bank_mask:0xf bound_ctrl:1
	ds_read_b128 v[124:127], v90 offset:0xa00
	s_nop 0
	v_add_f32_dpp v0, v0, v0 row_half_mirror row_mask:0xf bank_mask:0xf bound_ctrl:1
	ds_read2st64_b32 v[108:109], v89 offset0:196 offset1:197
	ds_read2st64_b64 v[100:103], v88 offset0:68 offset1:69
	v_add_f32_dpp v2, v0, v0 row_mirror row_mask:0xf bank_mask:0xf bound_ctrl:1
	v_add_f32_dpp v0, v0, v0 row_mirror row_mask:0xf bank_mask:0xf bound_ctrl:1
	s_nop 1
	v_permlane16_swap_b32_e32 v0, v2
	v_add_f32_e32 v0, v0, v2
	v_pk_fma_f32 v[52:53], v[104:105], v[0:1], v[54:55] op_sel_hi:[1,0,1]
	v_pk_mul_f32 v[118:119], v[52:53], v[4:5] op_sel_hi:[0,1]
	v_pk_fma_f32 v[118:119], v[52:53], v[6:7], v[118:119] op_sel:[1,0,0]
	v_pk_mul_f32 v[10:11], v[110:111], v[10:11] op_sel:[1,0]
	ds_read_b128 v[4:7], v90 offset:0x4c00
	v_add_f32_dpp v118, v118, v118 quad_perm:[1,0,3,2] row_mask:0xf bank_mask:0xf bound_ctrl:1
	v_add_f32_dpp v119, v119, v119 quad_perm:[1,0,3,2] row_mask:0xf bank_mask:0xf bound_ctrl:1
	v_pk_fma_f32 v[54:55], v[52:53], v[8:9], v[10:11]
	v_add_f32_dpp v118, v118, v118 quad_perm:[2,3,0,1] row_mask:0xf bank_mask:0xf bound_ctrl:1
	ds_read_b128 v[8:11], v90 offset:0xc00
	s_nop 0
	v_add_f32_dpp v118, v118, v118 row_half_mirror row_mask:0xf bank_mask:0xf bound_ctrl:1
	ds_write2_b32 v93, v1, v119 offset0:72 offset1:108
	s_nop 0
	v_add_f32_dpp v2, v118, v118 row_mirror row_mask:0xf bank_mask:0xf bound_ctrl:1
	v_add_f32_dpp v118, v118, v118 row_mirror row_mask:0xf bank_mask:0xf bound_ctrl:1
	s_nop 0
	s_waitcnt lgkmcnt(3)
	v_permlane16_swap_b32_e32 v118, v2
	v_add_f32_e32 v118, v118, v2
	v_pk_fma_f32 v[52:53], v[106:107], v[118:119], v[54:55] op_sel_hi:[1,0,1]
	v_pk_mul_f32 v[0:1], v[52:53], v[112:113] op_sel_hi:[0,1]
	v_pk_fma_f32 v[0:1], v[52:53], v[114:115], v[0:1] op_sel:[1,0,0]
	v_pk_mul_f32 v[98:99], v[108:109], v[98:99] op_sel_hi:[0,1]
	ds_read_b128 v[112:115], v90 offset:0x4e00
	v_add_f32_dpp v0, v0, v0 quad_perm:[1,0,3,2] row_mask:0xf bank_mask:0xf bound_ctrl:1
	v_add_f32_dpp v1, v1, v1 quad_perm:[1,0,3,2] row_mask:0xf bank_mask:0xf bound_ctrl:1
	v_pk_fma_f32 v[54:55], v[52:53], v[96:97], v[98:99]
	v_add_f32_dpp v0, v0, v0 quad_perm:[2,3,0,1] row_mask:0xf bank_mask:0xf bound_ctrl:1
	ds_read_b128 v[96:99], v90 offset:0xe00
	s_nop 0
	v_add_f32_dpp v0, v0, v0 row_half_mirror row_mask:0xf bank_mask:0xf bound_ctrl:1
	ds_read2st64_b32 v[110:111], v89 offset0:198 offset1:199
	ds_read2st64_b64 v[104:107], v88 offset0:70 offset1:71
	v_add_f32_dpp v2, v0, v0 row_mirror row_mask:0xf bank_mask:0xf bound_ctrl:1
	v_add_f32_dpp v0, v0, v0 row_mirror row_mask:0xf bank_mask:0xf bound_ctrl:1
	s_nop 1
	v_permlane16_swap_b32_e32 v0, v2
	v_add_f32_e32 v0, v0, v2
	v_pk_fma_f32 v[52:53], v[100:101], v[0:1], v[54:55] op_sel_hi:[1,0,1]
	v_pk_mul_f32 v[118:119], v[52:53], v[120:121] op_sel_hi:[0,1]
	v_pk_fma_f32 v[118:119], v[52:53], v[122:123], v[118:119] op_sel:[1,0,0]
	v_pk_mul_f32 v[126:127], v[108:109], v[126:127] op_sel:[1,0]
	ds_read_b128 v[120:123], v90 offset:0x5000
	v_add_f32_dpp v118, v118, v118 quad_perm:[1,0,3,2] row_mask:0xf bank_mask:0xf bound_ctrl:1
	v_add_f32_dpp v119, v119, v119 quad_perm:[1,0,3,2] row_mask:0xf bank_mask:0xf bound_ctrl:1
	v_pk_fma_f32 v[54:55], v[52:53], v[124:125], v[126:127]
	v_add_f32_dpp v118, v118, v118 quad_perm:[2,3,0,1] row_mask:0xf bank_mask:0xf bound_ctrl:1
	ds_read_b128 v[124:127], v90 offset:0x1000
	s_nop 0
	v_add_f32_dpp v118, v118, v118 row_half_mirror row_mask:0xf bank_mask:0xf bound_ctrl:1
	ds_write2_b32 v93, v1, v119 offset0:144 offset1:180
	s_nop 0
	v_add_f32_dpp v2, v118, v118 row_mirror row_mask:0xf bank_mask:0xf bound_ctrl:1
	v_add_f32_dpp v118, v118, v118 row_mirror row_mask:0xf bank_mask:0xf bound_ctrl:1
	s_nop 0
	s_waitcnt lgkmcnt(3)
	v_permlane16_swap_b32_e32 v118, v2
	v_add_f32_e32 v118, v118, v2
	v_pk_fma_f32 v[52:53], v[102:103], v[118:119], v[54:55] op_sel_hi:[1,0,1]
	v_pk_mul_f32 v[0:1], v[52:53], v[4:5] op_sel_hi:[0,1]
	v_pk_fma_f32 v[0:1], v[52:53], v[6:7], v[0:1] op_sel:[1,0,0]
	v_pk_mul_f32 v[10:11], v[110:111], v[10:11] op_sel_hi:[0,1]
	ds_read_b128 v[4:7], v90 offset:0x5200
	v_add_f32_dpp v0, v0, v0 quad_perm:[1,0,3,2] row_mask:0xf bank_mask:0xf bound_ctrl:1
	v_add_f32_dpp v1, v1, v1 quad_perm:[1,0,3,2] row_mask:0xf bank_mask:0xf bound_ctrl:1
	v_pk_fma_f32 v[54:55], v[52:53], v[8:9], v[10:11]
	v_add_f32_dpp v0, v0, v0 quad_perm:[2,3,0,1] row_mask:0xf bank_mask:0xf bound_ctrl:1
	ds_read_b128 v[8:11], v90 offset:0x1200
	s_nop 0
	v_add_f32_dpp v0, v0, v0 row_half_mirror row_mask:0xf bank_mask:0xf bound_ctrl:1
	ds_read2st64_b32 v[108:109], v89 offset0:200 offset1:201
	ds_read2st64_b64 v[100:103], v88 offset0:72 offset1:73
	v_add_f32_dpp v2, v0, v0 row_mirror row_mask:0xf bank_mask:0xf bound_ctrl:1
	v_add_f32_dpp v0, v0, v0 row_mirror row_mask:0xf bank_mask:0xf bound_ctrl:1
	s_nop 1
	v_permlane16_swap_b32_e32 v0, v2
	v_add_f32_e32 v0, v0, v2
	v_pk_fma_f32 v[52:53], v[104:105], v[0:1], v[54:55] op_sel_hi:[1,0,1]
	v_pk_mul_f32 v[118:119], v[52:53], v[112:113] op_sel_hi:[0,1]
	v_pk_fma_f32 v[118:119], v[52:53], v[114:115], v[118:119] op_sel:[1,0,0]
	v_pk_mul_f32 v[98:99], v[110:111], v[98:99] op_sel:[1,0]
	ds_read_b128 v[112:115], v90 offset:0x5400
	v_add_f32_dpp v118, v118, v118 quad_perm:[1,0,3,2] row_mask:0xf bank_mask:0xf bound_ctrl:1
	v_add_f32_dpp v119, v119, v119 quad_perm:[1,0,3,2] row_mask:0xf bank_mask:0xf bound_ctrl:1
	v_pk_fma_f32 v[54:55], v[52:53], v[96:97], v[98:99]
	v_add_f32_dpp v118, v118, v118 quad_perm:[2,3,0,1] row_mask:0xf bank_mask:0xf bound_ctrl:1
	ds_read_b128 v[96:99], v90 offset:0x1400
	s_nop 0
	v_add_f32_dpp v118, v118, v118 row_half_mirror row_mask:0xf bank_mask:0xf bound_ctrl:1
	ds_write2_b32 v93, v1, v119 offset0:216 offset1:252
	s_nop 0
	v_add_f32_dpp v2, v118, v118 row_mirror row_mask:0xf bank_mask:0xf bound_ctrl:1
	v_add_f32_dpp v118, v118, v118 row_mirror row_mask:0xf bank_mask:0xf bound_ctrl:1
	s_nop 0
	s_waitcnt lgkmcnt(3)
	v_permlane16_swap_b32_e32 v118, v2
	v_add_f32_e32 v118, v118, v2
	v_pk_fma_f32 v[52:53], v[106:107], v[118:119], v[54:55] op_sel_hi:[1,0,1]
	v_pk_mul_f32 v[0:1], v[52:53], v[120:121] op_sel_hi:[0,1]
	v_pk_fma_f32 v[0:1], v[52:53], v[122:123], v[0:1] op_sel:[1,0,0]
	v_pk_mul_f32 v[126:127], v[108:109], v[126:127] op_sel_hi:[0,1]
	ds_read_b128 v[120:123], v90 offset:0x5600
	v_add_f32_dpp v0, v0, v0 quad_perm:[1,0,3,2] row_mask:0xf bank_mask:0xf bound_ctrl:1
	v_add_f32_dpp v1, v1, v1 quad_perm:[1,0,3,2] row_mask:0xf bank_mask:0xf bound_ctrl:1
	v_pk_fma_f32 v[54:55], v[52:53], v[124:125], v[126:127]
	v_add_f32_dpp v0, v0, v0 quad_perm:[2,3,0,1] row_mask:0xf bank_mask:0xf bound_ctrl:1
	ds_read_b128 v[124:127], v90 offset:0x1600
	s_nop 0
	v_add_f32_dpp v0, v0, v0 row_half_mirror row_mask:0xf bank_mask:0xf bound_ctrl:1
	ds_read2st64_b32 v[110:111], v89 offset0:202 offset1:203
	ds_read2st64_b64 v[104:107], v88 offset0:74 offset1:75
	v_add_f32_dpp v2, v0, v0 row_mirror row_mask:0xf bank_mask:0xf bound_ctrl:1
	v_add_f32_dpp v0, v0, v0 row_mirror row_mask:0xf bank_mask:0xf bound_ctrl:1
	v_add_u32_e32 v93, 0x480, v93
	s_nop 0
	v_permlane16_swap_b32_e32 v0, v2
	v_add_f32_e32 v0, v0, v2
	v_pk_fma_f32 v[52:53], v[100:101], v[0:1], v[54:55] op_sel_hi:[1,0,1]
	v_pk_mul_f32 v[118:119], v[52:53], v[4:5] op_sel_hi:[0,1]
	v_pk_fma_f32 v[118:119], v[52:53], v[6:7], v[118:119] op_sel:[1,0,0]
	v_pk_mul_f32 v[10:11], v[108:109], v[10:11] op_sel:[1,0]
	ds_read_b128 v[4:7], v90 offset:0x5800
	v_add_f32_dpp v118, v118, v118 quad_perm:[1,0,3,2] row_mask:0xf bank_mask:0xf bound_ctrl:1
	v_add_f32_dpp v119, v119, v119 quad_perm:[1,0,3,2] row_mask:0xf bank_mask:0xf bound_ctrl:1
	v_pk_fma_f32 v[54:55], v[52:53], v[8:9], v[10:11]
	v_add_f32_dpp v118, v118, v118 quad_perm:[2,3,0,1] row_mask:0xf bank_mask:0xf bound_ctrl:1
	ds_read_b128 v[8:11], v90 offset:0x1800
	s_nop 0
	v_add_f32_dpp v118, v118, v118 row_half_mirror row_mask:0xf bank_mask:0xf bound_ctrl:1
	ds_write2_b32 v93, v1, v119 offset0:0 offset1:36
	s_nop 0
	v_add_f32_dpp v2, v118, v118 row_mirror row_mask:0xf bank_mask:0xf bound_ctrl:1
	v_add_f32_dpp v118, v118, v118 row_mirror row_mask:0xf bank_mask:0xf bound_ctrl:1
	s_nop 0
	s_waitcnt lgkmcnt(3)
	v_permlane16_swap_b32_e32 v118, v2
	v_add_f32_e32 v118, v118, v2
	v_pk_fma_f32 v[52:53], v[102:103], v[118:119], v[54:55] op_sel_hi:[1,0,1]
	v_pk_mul_f32 v[0:1], v[52:53], v[112:113] op_sel_hi:[0,1]
	v_pk_fma_f32 v[0:1], v[52:53], v[114:115], v[0:1] op_sel:[1,0,0]
	v_pk_mul_f32 v[98:99], v[110:111], v[98:99] op_sel_hi:[0,1]
	ds_read_b128 v[112:115], v90 offset:0x5a00
	v_add_f32_dpp v0, v0, v0 quad_perm:[1,0,3,2] row_mask:0xf bank_mask:0xf bound_ctrl:1
	v_add_f32_dpp v1, v1, v1 quad_perm:[1,0,3,2] row_mask:0xf bank_mask:0xf bound_ctrl:1
	v_pk_fma_f32 v[54:55], v[52:53], v[96:97], v[98:99]
	v_add_f32_dpp v0, v0, v0 quad_perm:[2,3,0,1] row_mask:0xf bank_mask:0xf bound_ctrl:1
	ds_read_b128 v[96:99], v90 offset:0x1a00
	s_nop 0
	v_add_f32_dpp v0, v0, v0 row_half_mirror row_mask:0xf bank_mask:0xf bound_ctrl:1
	ds_read2st64_b32 v[108:109], v89 offset0:204 offset1:205
	ds_read2st64_b64 v[100:103], v88 offset0:76 offset1:77
	v_add_f32_dpp v2, v0, v0 row_mirror row_mask:0xf bank_mask:0xf bound_ctrl:1
	v_add_f32_dpp v0, v0, v0 row_mirror row_mask:0xf bank_mask:0xf bound_ctrl:1
	s_nop 1
	v_permlane16_swap_b32_e32 v0, v2
	v_add_f32_e32 v0, v0, v2
	v_pk_fma_f32 v[52:53], v[104:105], v[0:1], v[54:55] op_sel_hi:[1,0,1]
	v_pk_mul_f32 v[118:119], v[52:53], v[120:121] op_sel_hi:[0,1]
	v_pk_fma_f32 v[118:119], v[52:53], v[122:123], v[118:119] op_sel:[1,0,0]
	v_pk_mul_f32 v[126:127], v[110:111], v[126:127] op_sel:[1,0]
	ds_read_b128 v[120:123], v90 offset:0x5c00
	v_add_f32_dpp v118, v118, v118 quad_perm:[1,0,3,2] row_mask:0xf bank_mask:0xf bound_ctrl:1
	v_add_f32_dpp v119, v119, v119 quad_perm:[1,0,3,2] row_mask:0xf bank_mask:0xf bound_ctrl:1
	v_pk_fma_f32 v[54:55], v[52:53], v[124:125], v[126:127]
	v_add_f32_dpp v118, v118, v118 quad_perm:[2,3,0,1] row_mask:0xf bank_mask:0xf bound_ctrl:1
	ds_read_b128 v[124:127], v90 offset:0x1c00
	s_nop 0
	v_add_f32_dpp v118, v118, v118 row_half_mirror row_mask:0xf bank_mask:0xf bound_ctrl:1
	ds_write2_b32 v93, v1, v119 offset0:72 offset1:108
	s_nop 0
	v_add_f32_dpp v2, v118, v118 row_mirror row_mask:0xf bank_mask:0xf bound_ctrl:1
	v_add_f32_dpp v118, v118, v118 row_mirror row_mask:0xf bank_mask:0xf bound_ctrl:1
	s_nop 0
	s_waitcnt lgkmcnt(3)
	v_permlane16_swap_b32_e32 v118, v2
	v_add_f32_e32 v118, v118, v2
	v_pk_fma_f32 v[52:53], v[106:107], v[118:119], v[54:55] op_sel_hi:[1,0,1]
	v_pk_mul_f32 v[0:1], v[52:53], v[4:5] op_sel_hi:[0,1]
	v_pk_fma_f32 v[0:1], v[52:53], v[6:7], v[0:1] op_sel:[1,0,0]
	v_pk_mul_f32 v[10:11], v[108:109], v[10:11] op_sel_hi:[0,1]
	ds_read_b128 v[4:7], v90 offset:0x5e00
	v_add_f32_dpp v0, v0, v0 quad_perm:[1,0,3,2] row_mask:0xf bank_mask:0xf bound_ctrl:1
	v_add_f32_dpp v1, v1, v1 quad_perm:[1,0,3,2] row_mask:0xf bank_mask:0xf bound_ctrl:1
	v_pk_fma_f32 v[54:55], v[52:53], v[8:9], v[10:11]
	v_add_f32_dpp v0, v0, v0 quad_perm:[2,3,0,1] row_mask:0xf bank_mask:0xf bound_ctrl:1
	ds_read_b128 v[8:11], v90 offset:0x1e00
	s_nop 0
	v_add_f32_dpp v0, v0, v0 row_half_mirror row_mask:0xf bank_mask:0xf bound_ctrl:1
	ds_read2st64_b32 v[110:111], v89 offset0:206 offset1:207
	ds_read2st64_b64 v[104:107], v88 offset0:78 offset1:79
	v_add_f32_dpp v2, v0, v0 row_mirror row_mask:0xf bank_mask:0xf bound_ctrl:1
	v_add_f32_dpp v0, v0, v0 row_mirror row_mask:0xf bank_mask:0xf bound_ctrl:1
	s_nop 1
	v_permlane16_swap_b32_e32 v0, v2
	v_add_f32_e32 v0, v0, v2
	v_pk_fma_f32 v[52:53], v[100:101], v[0:1], v[54:55] op_sel_hi:[1,0,1]
	v_pk_mul_f32 v[118:119], v[52:53], v[112:113] op_sel_hi:[0,1]
	v_pk_fma_f32 v[118:119], v[52:53], v[114:115], v[118:119] op_sel:[1,0,0]
	v_pk_mul_f32 v[98:99], v[108:109], v[98:99] op_sel:[1,0]
	ds_read_b128 v[112:115], v90 offset:0x6000
	v_add_f32_dpp v118, v118, v118 quad_perm:[1,0,3,2] row_mask:0xf bank_mask:0xf bound_ctrl:1
	v_add_f32_dpp v119, v119, v119 quad_perm:[1,0,3,2] row_mask:0xf bank_mask:0xf bound_ctrl:1
	v_pk_fma_f32 v[54:55], v[52:53], v[96:97], v[98:99]
	v_add_f32_dpp v118, v118, v118 quad_perm:[2,3,0,1] row_mask:0xf bank_mask:0xf bound_ctrl:1
	ds_read_b128 v[96:99], v90 offset:0x2000
	s_nop 0
	v_add_f32_dpp v118, v118, v118 row_half_mirror row_mask:0xf bank_mask:0xf bound_ctrl:1
	ds_write2_b32 v93, v1, v119 offset0:144 offset1:180
	s_nop 0
	v_add_f32_dpp v2, v118, v118 row_mirror row_mask:0xf bank_mask:0xf bound_ctrl:1
	v_add_f32_dpp v118, v118, v118 row_mirror row_mask:0xf bank_mask:0xf bound_ctrl:1
	s_nop 0
	s_waitcnt lgkmcnt(3)
	v_permlane16_swap_b32_e32 v118, v2
	v_add_f32_e32 v118, v118, v2
	v_pk_fma_f32 v[52:53], v[102:103], v[118:119], v[54:55] op_sel_hi:[1,0,1]
	v_pk_mul_f32 v[0:1], v[52:53], v[120:121] op_sel_hi:[0,1]
	v_pk_fma_f32 v[0:1], v[52:53], v[122:123], v[0:1] op_sel:[1,0,0]
	v_pk_mul_f32 v[126:127], v[110:111], v[126:127] op_sel_hi:[0,1]
	ds_read_b128 v[120:123], v90 offset:0x6200
	v_add_f32_dpp v0, v0, v0 quad_perm:[1,0,3,2] row_mask:0xf bank_mask:0xf bound_ctrl:1
	v_add_f32_dpp v1, v1, v1 quad_perm:[1,0,3,2] row_mask:0xf bank_mask:0xf bound_ctrl:1
	v_pk_fma_f32 v[54:55], v[52:53], v[124:125], v[126:127]
	v_add_f32_dpp v0, v0, v0 quad_perm:[2,3,0,1] row_mask:0xf bank_mask:0xf bound_ctrl:1
	ds_read_b128 v[124:127], v90 offset:0x2200
	s_nop 0
	v_add_f32_dpp v0, v0, v0 row_half_mirror row_mask:0xf bank_mask:0xf bound_ctrl:1
	ds_read2st64_b32 v[108:109], v89 offset0:208 offset1:209
	ds_read2st64_b64 v[100:103], v88 offset0:80 offset1:81
	v_add_f32_dpp v2, v0, v0 row_mirror row_mask:0xf bank_mask:0xf bound_ctrl:1
	v_add_f32_dpp v0, v0, v0 row_mirror row_mask:0xf bank_mask:0xf bound_ctrl:1
	s_nop 1
	v_permlane16_swap_b32_e32 v0, v2
	v_add_f32_e32 v0, v0, v2
	v_pk_fma_f32 v[52:53], v[104:105], v[0:1], v[54:55] op_sel_hi:[1,0,1]
	v_pk_mul_f32 v[118:119], v[52:53], v[4:5] op_sel_hi:[0,1]
	v_pk_fma_f32 v[118:119], v[52:53], v[6:7], v[118:119] op_sel:[1,0,0]
	v_pk_mul_f32 v[10:11], v[110:111], v[10:11] op_sel:[1,0]
	ds_read_b128 v[4:7], v90 offset:0x6400
	v_add_f32_dpp v118, v118, v118 quad_perm:[1,0,3,2] row_mask:0xf bank_mask:0xf bound_ctrl:1
	v_add_f32_dpp v119, v119, v119 quad_perm:[1,0,3,2] row_mask:0xf bank_mask:0xf bound_ctrl:1
	v_pk_fma_f32 v[54:55], v[52:53], v[8:9], v[10:11]
	v_add_f32_dpp v118, v118, v118 quad_perm:[2,3,0,1] row_mask:0xf bank_mask:0xf bound_ctrl:1
	ds_read_b128 v[8:11], v90 offset:0x2400
	s_nop 0
	v_add_f32_dpp v118, v118, v118 row_half_mirror row_mask:0xf bank_mask:0xf bound_ctrl:1
	ds_write2_b32 v93, v1, v119 offset0:216 offset1:252
	s_nop 0
	v_add_f32_dpp v2, v118, v118 row_mirror row_mask:0xf bank_mask:0xf bound_ctrl:1
	v_add_f32_dpp v118, v118, v118 row_mirror row_mask:0xf bank_mask:0xf bound_ctrl:1
	s_nop 0
	s_waitcnt lgkmcnt(3)
	v_permlane16_swap_b32_e32 v118, v2
	v_add_f32_e32 v118, v118, v2
	v_pk_fma_f32 v[52:53], v[106:107], v[118:119], v[54:55] op_sel_hi:[1,0,1]
	s_cmp_eq_u32 s88, 0x800000
	s_cbranch_scc1 .LBB0_684
	v_pk_mul_f32 v[0:1], v[52:53], v[112:113] op_sel_hi:[0,1]
	v_pk_fma_f32 v[0:1], v[52:53], v[114:115], v[0:1] op_sel:[1,0,0]
	v_pk_mul_f32 v[98:99], v[108:109], v[98:99] op_sel_hi:[0,1]
	ds_read_b128 v[112:115], v90 offset:0x6600
	v_add_f32_dpp v0, v0, v0 quad_perm:[1,0,3,2] row_mask:0xf bank_mask:0xf bound_ctrl:1
	v_add_f32_dpp v1, v1, v1 quad_perm:[1,0,3,2] row_mask:0xf bank_mask:0xf bound_ctrl:1
	v_pk_fma_f32 v[54:55], v[52:53], v[96:97], v[98:99]
	v_add_f32_dpp v0, v0, v0 quad_perm:[2,3,0,1] row_mask:0xf bank_mask:0xf bound_ctrl:1
	ds_read_b128 v[96:99], v90 offset:0x2600
	s_nop 0
	v_add_f32_dpp v0, v0, v0 row_half_mirror row_mask:0xf bank_mask:0xf bound_ctrl:1
	ds_read2st64_b32 v[110:111], v89 offset0:210 offset1:211
	ds_read2st64_b64 v[104:107], v88 offset0:82 offset1:83
	v_add_f32_dpp v2, v0, v0 row_mirror row_mask:0xf bank_mask:0xf bound_ctrl:1
	v_add_f32_dpp v0, v0, v0 row_mirror row_mask:0xf bank_mask:0xf bound_ctrl:1
	v_add_u32_e32 v93, 0x480, v93
	s_nop 0
	v_permlane16_swap_b32_e32 v0, v2
	v_add_f32_e32 v0, v0, v2
	v_pk_fma_f32 v[52:53], v[100:101], v[0:1], v[54:55] op_sel_hi:[1,0,1]
	v_pk_mul_f32 v[118:119], v[52:53], v[120:121] op_sel_hi:[0,1]
	v_pk_fma_f32 v[118:119], v[52:53], v[122:123], v[118:119] op_sel:[1,0,0]
	v_pk_mul_f32 v[126:127], v[108:109], v[126:127] op_sel:[1,0]
	ds_read_b128 v[120:123], v90 offset:0x6800
	v_add_f32_dpp v118, v118, v118 quad_perm:[1,0,3,2] row_mask:0xf bank_mask:0xf bound_ctrl:1
	v_add_f32_dpp v119, v119, v119 quad_perm:[1,0,3,2] row_mask:0xf bank_mask:0xf bound_ctrl:1
	v_pk_fma_f32 v[54:55], v[52:53], v[124:125], v[126:127]
	v_add_f32_dpp v118, v118, v118 quad_perm:[2,3,0,1] row_mask:0xf bank_mask:0xf bound_ctrl:1
	ds_read_b128 v[124:127], v90 offset:0x2800
	s_nop 0
	v_add_f32_dpp v118, v118, v118 row_half_mirror row_mask:0xf bank_mask:0xf bound_ctrl:1
	ds_write2_b32 v93, v1, v119 offset0:0 offset1:36
	s_nop 0
	v_add_f32_dpp v2, v118, v118 row_mirror row_mask:0xf bank_mask:0xf bound_ctrl:1
	v_add_f32_dpp v118, v118, v118 row_mirror row_mask:0xf bank_mask:0xf bound_ctrl:1
	s_nop 0
	s_waitcnt lgkmcnt(3)
	v_permlane16_swap_b32_e32 v118, v2
	v_add_f32_e32 v118, v118, v2
	v_pk_fma_f32 v[52:53], v[102:103], v[118:119], v[54:55] op_sel_hi:[1,0,1]
	v_pk_mul_f32 v[0:1], v[52:53], v[4:5] op_sel_hi:[0,1]
	v_pk_fma_f32 v[0:1], v[52:53], v[6:7], v[0:1] op_sel:[1,0,0]
	v_pk_mul_f32 v[10:11], v[110:111], v[10:11] op_sel_hi:[0,1]
	ds_read_b128 v[4:7], v90 offset:0x6a00
	v_add_f32_dpp v0, v0, v0 quad_perm:[1,0,3,2] row_mask:0xf bank_mask:0xf bound_ctrl:1
	v_add_f32_dpp v1, v1, v1 quad_perm:[1,0,3,2] row_mask:0xf bank_mask:0xf bound_ctrl:1
	v_pk_fma_f32 v[54:55], v[52:53], v[8:9], v[10:11]
	v_add_f32_dpp v0, v0, v0 quad_perm:[2,3,0,1] row_mask:0xf bank_mask:0xf bound_ctrl:1
	ds_read_b128 v[8:11], v90 offset:0x2a00
	s_nop 0
	v_add_f32_dpp v0, v0, v0 row_half_mirror row_mask:0xf bank_mask:0xf bound_ctrl:1
	ds_read2st64_b32 v[108:109], v89 offset0:212 offset1:213
	ds_read2st64_b64 v[100:103], v88 offset0:84 offset1:85
	v_add_f32_dpp v2, v0, v0 row_mirror row_mask:0xf bank_mask:0xf bound_ctrl:1
	v_add_f32_dpp v0, v0, v0 row_mirror row_mask:0xf bank_mask:0xf bound_ctrl:1
	s_nop 1
	v_permlane16_swap_b32_e32 v0, v2
	v_add_f32_e32 v0, v0, v2
	v_pk_fma_f32 v[52:53], v[104:105], v[0:1], v[54:55] op_sel_hi:[1,0,1]
	v_pk_mul_f32 v[118:119], v[52:53], v[112:113] op_sel_hi:[0,1]
	v_pk_fma_f32 v[118:119], v[52:53], v[114:115], v[118:119] op_sel:[1,0,0]
	v_pk_mul_f32 v[98:99], v[110:111], v[98:99] op_sel:[1,0]
	ds_read_b128 v[112:115], v90 offset:0x6c00
	v_add_f32_dpp v118, v118, v118 quad_perm:[1,0,3,2] row_mask:0xf bank_mask:0xf bound_ctrl:1
	v_add_f32_dpp v119, v119, v119 quad_perm:[1,0,3,2] row_mask:0xf bank_mask:0xf bound_ctrl:1
	v_pk_fma_f32 v[54:55], v[52:53], v[96:97], v[98:99]
	v_add_f32_dpp v118, v118, v118 quad_perm:[2,3,0,1] row_mask:0xf bank_mask:0xf bound_ctrl:1
	ds_read_b128 v[96:99], v90 offset:0x2c00
	s_nop 0
	v_add_f32_dpp v118, v118, v118 row_half_mirror row_mask:0xf bank_mask:0xf bound_ctrl:1
	ds_write2_b32 v93, v1, v119 offset0:72 offset1:108
	s_nop 0
	v_add_f32_dpp v2, v118, v118 row_mirror row_mask:0xf bank_mask:0xf bound_ctrl:1
	v_add_f32_dpp v118, v118, v118 row_mirror row_mask:0xf bank_mask:0xf bound_ctrl:1
	s_nop 0
	s_waitcnt lgkmcnt(3)
	v_permlane16_swap_b32_e32 v118, v2
	v_add_f32_e32 v118, v118, v2
	v_pk_fma_f32 v[52:53], v[106:107], v[118:119], v[54:55] op_sel_hi:[1,0,1]
	v_pk_mul_f32 v[0:1], v[52:53], v[120:121] op_sel_hi:[0,1]
	v_pk_fma_f32 v[0:1], v[52:53], v[122:123], v[0:1] op_sel:[1,0,0]
	v_pk_mul_f32 v[126:127], v[108:109], v[126:127] op_sel_hi:[0,1]
	ds_read_b128 v[120:123], v90 offset:0x6e00
	v_add_f32_dpp v0, v0, v0 quad_perm:[1,0,3,2] row_mask:0xf bank_mask:0xf bound_ctrl:1
	v_add_f32_dpp v1, v1, v1 quad_perm:[1,0,3,2] row_mask:0xf bank_mask:0xf bound_ctrl:1
	v_pk_fma_f32 v[54:55], v[52:53], v[124:125], v[126:127]
	v_add_f32_dpp v0, v0, v0 quad_perm:[2,3,0,1] row_mask:0xf bank_mask:0xf bound_ctrl:1
	ds_read_b128 v[124:127], v90 offset:0x2e00
	s_nop 0
	v_add_f32_dpp v0, v0, v0 row_half_mirror row_mask:0xf bank_mask:0xf bound_ctrl:1
	ds_read2st64_b32 v[110:111], v89 offset0:214 offset1:215
	ds_read2st64_b64 v[104:107], v88 offset0:86 offset1:87
	v_add_f32_dpp v2, v0, v0 row_mirror row_mask:0xf bank_mask:0xf bound_ctrl:1
	v_add_f32_dpp v0, v0, v0 row_mirror row_mask:0xf bank_mask:0xf bound_ctrl:1
	s_nop 1
	v_permlane16_swap_b32_e32 v0, v2
	v_add_f32_e32 v0, v0, v2
	v_pk_fma_f32 v[52:53], v[100:101], v[0:1], v[54:55] op_sel_hi:[1,0,1]
	v_pk_mul_f32 v[118:119], v[52:53], v[4:5] op_sel_hi:[0,1]
	v_pk_fma_f32 v[118:119], v[52:53], v[6:7], v[118:119] op_sel:[1,0,0]
	v_pk_mul_f32 v[10:11], v[108:109], v[10:11] op_sel:[1,0]
	ds_read_b128 v[4:7], v90 offset:0x7000
	v_add_f32_dpp v118, v118, v118 quad_perm:[1,0,3,2] row_mask:0xf bank_mask:0xf bound_ctrl:1
	v_add_f32_dpp v119, v119, v119 quad_perm:[1,0,3,2] row_mask:0xf bank_mask:0xf bound_ctrl:1
	v_pk_fma_f32 v[54:55], v[52:53], v[8:9], v[10:11]
	v_add_f32_dpp v118, v118, v118 quad_perm:[2,3,0,1] row_mask:0xf bank_mask:0xf bound_ctrl:1
	ds_read_b128 v[8:11], v90 offset:0x3000
	s_nop 0
	v_add_f32_dpp v118, v118, v118 row_half_mirror row_mask:0xf bank_mask:0xf bound_ctrl:1
	ds_write2_b32 v93, v1, v119 offset0:144 offset1:180
	s_nop 0
	v_add_f32_dpp v2, v118, v118 row_mirror row_mask:0xf bank_mask:0xf bound_ctrl:1
	v_add_f32_dpp v118, v118, v118 row_mirror row_mask:0xf bank_mask:0xf bound_ctrl:1
	s_nop 0
	s_waitcnt lgkmcnt(3)
	v_permlane16_swap_b32_e32 v118, v2
	v_add_f32_e32 v118, v118, v2
	v_pk_fma_f32 v[52:53], v[102:103], v[118:119], v[54:55] op_sel_hi:[1,0,1]
	v_pk_mul_f32 v[0:1], v[52:53], v[112:113] op_sel_hi:[0,1]
	v_pk_fma_f32 v[0:1], v[52:53], v[114:115], v[0:1] op_sel:[1,0,0]
	v_pk_mul_f32 v[98:99], v[110:111], v[98:99] op_sel_hi:[0,1]
	ds_read_b128 v[112:115], v90 offset:0x7200
	v_add_f32_dpp v0, v0, v0 quad_perm:[1,0,3,2] row_mask:0xf bank_mask:0xf bound_ctrl:1
	v_add_f32_dpp v1, v1, v1 quad_perm:[1,0,3,2] row_mask:0xf bank_mask:0xf bound_ctrl:1
	v_pk_fma_f32 v[54:55], v[52:53], v[96:97], v[98:99]
	v_add_f32_dpp v0, v0, v0 quad_perm:[2,3,0,1] row_mask:0xf bank_mask:0xf bound_ctrl:1
	ds_read_b128 v[96:99], v90 offset:0x3200
	s_nop 0
	v_add_f32_dpp v0, v0, v0 row_half_mirror row_mask:0xf bank_mask:0xf bound_ctrl:1
	ds_read2st64_b32 v[108:109], v89 offset0:216 offset1:217
	ds_read2st64_b64 v[100:103], v88 offset0:88 offset1:89
	v_add_f32_dpp v2, v0, v0 row_mirror row_mask:0xf bank_mask:0xf bound_ctrl:1
	v_add_f32_dpp v0, v0, v0 row_mirror row_mask:0xf bank_mask:0xf bound_ctrl:1
	s_nop 1
	v_permlane16_swap_b32_e32 v0, v2
	v_add_f32_e32 v0, v0, v2
	v_pk_fma_f32 v[52:53], v[104:105], v[0:1], v[54:55] op_sel_hi:[1,0,1]
	v_pk_mul_f32 v[118:119], v[52:53], v[120:121] op_sel_hi:[0,1]
	v_pk_fma_f32 v[118:119], v[52:53], v[122:123], v[118:119] op_sel:[1,0,0]
	v_pk_mul_f32 v[126:127], v[110:111], v[126:127] op_sel:[1,0]
	ds_read_b128 v[120:123], v90 offset:0x7400
	v_add_f32_dpp v118, v118, v118 quad_perm:[1,0,3,2] row_mask:0xf bank_mask:0xf bound_ctrl:1
	v_add_f32_dpp v119, v119, v119 quad_perm:[1,0,3,2] row_mask:0xf bank_mask:0xf bound_ctrl:1
	v_pk_fma_f32 v[54:55], v[52:53], v[124:125], v[126:127]
	v_add_f32_dpp v118, v118, v118 quad_perm:[2,3,0,1] row_mask:0xf bank_mask:0xf bound_ctrl:1
	ds_read_b128 v[124:127], v90 offset:0x3400
	s_nop 0
	v_add_f32_dpp v118, v118, v118 row_half_mirror row_mask:0xf bank_mask:0xf bound_ctrl:1
	ds_write2_b32 v93, v1, v119 offset0:216 offset1:252
	s_nop 0
	v_add_f32_dpp v2, v118, v118 row_mirror row_mask:0xf bank_mask:0xf bound_ctrl:1
	v_add_f32_dpp v118, v118, v118 row_mirror row_mask:0xf bank_mask:0xf bound_ctrl:1
	s_nop 0
	s_waitcnt lgkmcnt(3)
	v_permlane16_swap_b32_e32 v118, v2
	v_add_f32_e32 v118, v118, v2
	v_pk_fma_f32 v[52:53], v[106:107], v[118:119], v[54:55] op_sel_hi:[1,0,1]
	v_pk_mul_f32 v[0:1], v[52:53], v[4:5] op_sel_hi:[0,1]
	v_pk_fma_f32 v[0:1], v[52:53], v[6:7], v[0:1] op_sel:[1,0,0]
	v_pk_mul_f32 v[10:11], v[108:109], v[10:11] op_sel_hi:[0,1]
	ds_read_b128 v[4:7], v90 offset:0x7600
	v_add_f32_dpp v0, v0, v0 quad_perm:[1,0,3,2] row_mask:0xf bank_mask:0xf bound_ctrl:1
	v_add_f32_dpp v1, v1, v1 quad_perm:[1,0,3,2] row_mask:0xf bank_mask:0xf bound_ctrl:1
	v_pk_fma_f32 v[54:55], v[52:53], v[8:9], v[10:11]
	v_add_f32_dpp v0, v0, v0 quad_perm:[2,3,0,1] row_mask:0xf bank_mask:0xf bound_ctrl:1
	ds_read_b128 v[8:11], v90 offset:0x3600
	s_nop 0
	v_add_f32_dpp v0, v0, v0 row_half_mirror row_mask:0xf bank_mask:0xf bound_ctrl:1
	ds_read2st64_b32 v[110:111], v89 offset0:218 offset1:219
	ds_read2st64_b64 v[104:107], v88 offset0:90 offset1:91
	v_add_f32_dpp v2, v0, v0 row_mirror row_mask:0xf bank_mask:0xf bound_ctrl:1
	v_add_f32_dpp v0, v0, v0 row_mirror row_mask:0xf bank_mask:0xf bound_ctrl:1
	v_add_u32_e32 v93, 0x480, v93
	s_nop 0
	v_permlane16_swap_b32_e32 v0, v2
	v_add_f32_e32 v0, v0, v2
	v_pk_fma_f32 v[52:53], v[100:101], v[0:1], v[54:55] op_sel_hi:[1,0,1]
	v_pk_mul_f32 v[118:119], v[52:53], v[112:113] op_sel_hi:[0,1]
	v_pk_fma_f32 v[118:119], v[52:53], v[114:115], v[118:119] op_sel:[1,0,0]
	v_pk_mul_f32 v[98:99], v[108:109], v[98:99] op_sel:[1,0]
	ds_read_b128 v[112:115], v90 offset:0x7800
	v_add_f32_dpp v118, v118, v118 quad_perm:[1,0,3,2] row_mask:0xf bank_mask:0xf bound_ctrl:1
	v_add_f32_dpp v119, v119, v119 quad_perm:[1,0,3,2] row_mask:0xf bank_mask:0xf bound_ctrl:1
	v_pk_fma_f32 v[54:55], v[52:53], v[96:97], v[98:99]
	v_add_f32_dpp v118, v118, v118 quad_perm:[2,3,0,1] row_mask:0xf bank_mask:0xf bound_ctrl:1
	ds_read_b128 v[96:99], v90 offset:0x3800
	s_nop 0
	v_add_f32_dpp v118, v118, v118 row_half_mirror row_mask:0xf bank_mask:0xf bound_ctrl:1
	ds_write2_b32 v93, v1, v119 offset0:0 offset1:36
	s_nop 0
	v_add_f32_dpp v2, v118, v118 row_mirror row_mask:0xf bank_mask:0xf bound_ctrl:1
	v_add_f32_dpp v118, v118, v118 row_mirror row_mask:0xf bank_mask:0xf bound_ctrl:1
	s_nop 0
	s_waitcnt lgkmcnt(3)
	v_permlane16_swap_b32_e32 v118, v2
	v_add_f32_e32 v118, v118, v2
	v_pk_fma_f32 v[52:53], v[102:103], v[118:119], v[54:55] op_sel_hi:[1,0,1]
	v_pk_mul_f32 v[0:1], v[52:53], v[120:121] op_sel_hi:[0,1]
	v_pk_fma_f32 v[0:1], v[52:53], v[122:123], v[0:1] op_sel:[1,0,0]
	v_pk_mul_f32 v[126:127], v[110:111], v[126:127] op_sel_hi:[0,1]
	ds_read_b128 v[120:123], v90 offset:0x7a00
	v_add_f32_dpp v0, v0, v0 quad_perm:[1,0,3,2] row_mask:0xf bank_mask:0xf bound_ctrl:1
	v_add_f32_dpp v1, v1, v1 quad_perm:[1,0,3,2] row_mask:0xf bank_mask:0xf bound_ctrl:1
	v_pk_fma_f32 v[54:55], v[52:53], v[124:125], v[126:127]
	v_add_f32_dpp v0, v0, v0 quad_perm:[2,3,0,1] row_mask:0xf bank_mask:0xf bound_ctrl:1
	ds_read_b128 v[124:127], v90 offset:0x3a00
	s_nop 0
	v_add_f32_dpp v0, v0, v0 row_half_mirror row_mask:0xf bank_mask:0xf bound_ctrl:1
	ds_read2st64_b32 v[108:109], v89 offset0:220 offset1:221
	ds_read2st64_b64 v[100:103], v88 offset0:92 offset1:93
	v_add_f32_dpp v2, v0, v0 row_mirror row_mask:0xf bank_mask:0xf bound_ctrl:1
	v_add_f32_dpp v0, v0, v0 row_mirror row_mask:0xf bank_mask:0xf bound_ctrl:1
	s_nop 1
	v_permlane16_swap_b32_e32 v0, v2
	v_add_f32_e32 v0, v0, v2
	v_pk_fma_f32 v[52:53], v[104:105], v[0:1], v[54:55] op_sel_hi:[1,0,1]
	v_pk_mul_f32 v[118:119], v[52:53], v[4:5] op_sel_hi:[0,1]
	v_pk_fma_f32 v[118:119], v[52:53], v[6:7], v[118:119] op_sel:[1,0,0]
	v_pk_mul_f32 v[10:11], v[110:111], v[10:11] op_sel:[1,0]
	ds_read_b128 v[4:7], v90 offset:0x7c00
	v_add_f32_dpp v118, v118, v118 quad_perm:[1,0,3,2] row_mask:0xf bank_mask:0xf bound_ctrl:1
	v_add_f32_dpp v119, v119, v119 quad_perm:[1,0,3,2] row_mask:0xf bank_mask:0xf bound_ctrl:1
	v_pk_fma_f32 v[54:55], v[52:53], v[8:9], v[10:11]
	v_add_f32_dpp v118, v118, v118 quad_perm:[2,3,0,1] row_mask:0xf bank_mask:0xf bound_ctrl:1
	ds_read_b128 v[8:11], v90 offset:0x3c00
	s_nop 0
	v_add_f32_dpp v118, v118, v118 row_half_mirror row_mask:0xf bank_mask:0xf bound_ctrl:1
	ds_write2_b32 v93, v1, v119 offset0:72 offset1:108
	s_nop 0
	v_add_f32_dpp v2, v118, v118 row_mirror row_mask:0xf bank_mask:0xf bound_ctrl:1
	v_add_f32_dpp v118, v118, v118 row_mirror row_mask:0xf bank_mask:0xf bound_ctrl:1
	s_nop 0
	s_waitcnt lgkmcnt(3)
	v_permlane16_swap_b32_e32 v118, v2
	v_add_f32_e32 v118, v118, v2
	v_pk_fma_f32 v[52:53], v[106:107], v[118:119], v[54:55] op_sel_hi:[1,0,1]
	v_pk_mul_f32 v[0:1], v[52:53], v[112:113] op_sel_hi:[0,1]
	v_pk_fma_f32 v[0:1], v[52:53], v[114:115], v[0:1] op_sel:[1,0,0]
	v_pk_mul_f32 v[98:99], v[108:109], v[98:99] op_sel_hi:[0,1]
	ds_read_b128 v[112:115], v90 offset:0x7e00
	v_add_f32_dpp v0, v0, v0 quad_perm:[1,0,3,2] row_mask:0xf bank_mask:0xf bound_ctrl:1
	v_add_f32_dpp v1, v1, v1 quad_perm:[1,0,3,2] row_mask:0xf bank_mask:0xf bound_ctrl:1
	v_pk_fma_f32 v[54:55], v[52:53], v[96:97], v[98:99]
	v_add_f32_dpp v0, v0, v0 quad_perm:[2,3,0,1] row_mask:0xf bank_mask:0xf bound_ctrl:1
	ds_read_b128 v[96:99], v90 offset:0x3e00
	s_nop 0
	v_add_f32_dpp v0, v0, v0 row_half_mirror row_mask:0xf bank_mask:0xf bound_ctrl:1
	ds_read2st64_b32 v[110:111], v89 offset0:222 offset1:223
	ds_read2st64_b64 v[104:107], v88 offset0:94 offset1:95
	v_add_f32_dpp v2, v0, v0 row_mirror row_mask:0xf bank_mask:0xf bound_ctrl:1
	v_add_f32_dpp v0, v0, v0 row_mirror row_mask:0xf bank_mask:0xf bound_ctrl:1
	s_nop 1
	v_permlane16_swap_b32_e32 v0, v2
	v_add_f32_e32 v0, v0, v2
	v_pk_fma_f32 v[52:53], v[100:101], v[0:1], v[54:55] op_sel_hi:[1,0,1]
	v_pk_mul_f32 v[118:119], v[52:53], v[120:121] op_sel_hi:[0,1]
	v_pk_fma_f32 v[118:119], v[52:53], v[122:123], v[118:119] op_sel:[1,0,0]
	v_pk_mul_f32 v[126:127], v[108:109], v[126:127] op_sel:[1,0]
	s_nop 0
	v_add_f32_dpp v118, v118, v118 quad_perm:[1,0,3,2] row_mask:0xf bank_mask:0xf bound_ctrl:1
	v_add_f32_dpp v119, v119, v119 quad_perm:[1,0,3,2] row_mask:0xf bank_mask:0xf bound_ctrl:1
	v_pk_fma_f32 v[54:55], v[52:53], v[124:125], v[126:127]
	v_add_f32_dpp v118, v118, v118 quad_perm:[2,3,0,1] row_mask:0xf bank_mask:0xf bound_ctrl:1
	s_nop 0
	s_nop 0
	v_add_f32_dpp v118, v118, v118 row_half_mirror row_mask:0xf bank_mask:0xf bound_ctrl:1
	ds_write2_b32 v93, v1, v119 offset0:144 offset1:180
	s_nop 0
	v_add_f32_dpp v2, v118, v118 row_mirror row_mask:0xf bank_mask:0xf bound_ctrl:1
	v_add_f32_dpp v118, v118, v118 row_mirror row_mask:0xf bank_mask:0xf bound_ctrl:1
	s_nop 0
	s_waitcnt lgkmcnt(1)
	v_permlane16_swap_b32_e32 v118, v2
	v_add_f32_e32 v118, v118, v2
	v_pk_fma_f32 v[52:53], v[102:103], v[118:119], v[54:55] op_sel_hi:[1,0,1]
	v_pk_mul_f32 v[0:1], v[52:53], v[4:5] op_sel_hi:[0,1]
	v_pk_fma_f32 v[0:1], v[52:53], v[6:7], v[0:1] op_sel:[1,0,0]
	v_pk_mul_f32 v[10:11], v[110:111], v[10:11] op_sel_hi:[0,1]
	s_nop 0
	v_add_f32_dpp v0, v0, v0 quad_perm:[1,0,3,2] row_mask:0xf bank_mask:0xf bound_ctrl:1
	v_add_f32_dpp v1, v1, v1 quad_perm:[1,0,3,2] row_mask:0xf bank_mask:0xf bound_ctrl:1
	v_pk_fma_f32 v[54:55], v[52:53], v[8:9], v[10:11]
	v_add_f32_dpp v0, v0, v0 quad_perm:[2,3,0,1] row_mask:0xf bank_mask:0xf bound_ctrl:1
	s_nop 0
	s_nop 0
	v_add_f32_dpp v0, v0, v0 row_half_mirror row_mask:0xf bank_mask:0xf bound_ctrl:1
	s_nop 0
	s_nop 0
	v_add_f32_dpp v2, v0, v0 row_mirror row_mask:0xf bank_mask:0xf bound_ctrl:1
	v_add_f32_dpp v0, v0, v0 row_mirror row_mask:0xf bank_mask:0xf bound_ctrl:1
	s_nop 1
	v_permlane16_swap_b32_e32 v0, v2
	v_add_f32_e32 v0, v0, v2
	v_pk_fma_f32 v[52:53], v[104:105], v[0:1], v[54:55] op_sel_hi:[1,0,1]
	v_pk_mul_f32 v[118:119], v[52:53], v[112:113] op_sel_hi:[0,1]
	v_pk_fma_f32 v[118:119], v[52:53], v[114:115], v[118:119] op_sel:[1,0,0]
	v_pk_mul_f32 v[98:99], v[110:111], v[98:99] op_sel:[1,0]
	s_nop 0
	v_add_f32_dpp v118, v118, v118 quad_perm:[1,0,3,2] row_mask:0xf bank_mask:0xf bound_ctrl:1
	v_add_f32_dpp v119, v119, v119 quad_perm:[1,0,3,2] row_mask:0xf bank_mask:0xf bound_ctrl:1
	v_pk_fma_f32 v[54:55], v[52:53], v[96:97], v[98:99]
	v_add_f32_dpp v118, v118, v118 quad_perm:[2,3,0,1] row_mask:0xf bank_mask:0xf bound_ctrl:1
	s_nop 0
	s_nop 0
	v_add_f32_dpp v118, v118, v118 row_half_mirror row_mask:0xf bank_mask:0xf bound_ctrl:1
	ds_write2_b32 v93, v1, v119 offset0:216 offset1:252
	s_nop 0
	v_add_f32_dpp v2, v118, v118 row_mirror row_mask:0xf bank_mask:0xf bound_ctrl:1
	v_add_f32_dpp v118, v118, v118 row_mirror row_mask:0xf bank_mask:0xf bound_ctrl:1
	s_nop 0
	s_nop 0
	v_permlane16_swap_b32_e32 v118, v2
	v_add_f32_e32 v118, v118, v2
	v_pk_fma_f32 v[52:53], v[106:107], v[118:119], v[54:55] op_sel_hi:[1,0,1]
